# v34 + panel_rs_fill: four rowss loads issued together (one latency instead of four serialized vmcnt0 round trips)
# speedup vs baseline: 1.0163x; 1.0002x over previous
; #define LAS __attribute__((address_space(3)))
; __device__ __forceinline__ void panel_rs_fill(const float* rowss, int pm, LAS float* rs_lds, int tid) {
;     if (tid < 256) {
;         const float* p = rowss + (size_t)(pm * 256 + tid) * 16; float sacc = 0.f;
; #pragma unroll
;         for (int q = 0; q < 4; ++q) { const f32x4 a = *(const f32x4*)(p + 4 * q); sacc += (a[0] + a[1]) + (a[2] + a[3]); asm volatile("" : "+v"(sacc)); }
;         rs_lds[tid] = __builtin_amdgcn_rsqf(sacc * (1.f / 1024.f) + EPS);
;     }
;     asm volatile("s_waitcnt lgkmcnt(0)" ::: "memory"); __builtin_amdgcn_s_barrier(); asm volatile("" ::: "memory");
;     if (tid == 0) ((volatile LAS int*)rs_lds)[256] = pm;
; }
.LBB0_405:
	s_cmp_eq_u32 s93, 1
	s_mov_b64 s[10:11], -1
	s_cbranch_scc1 .LBB0_413
	v_mov_b32_e32 v128, s46
	ds_read_b32 v128, v128 offset:1024
	s_waitcnt lgkmcnt(0)
	v_cmp_eq_u32_e32 vcc, s94, v128
	s_cbranch_vccnz .LBB0_412
	s_mov_b64 s[10:11], exec
	v_readlane_b32 s4, v226, 35
	v_readlane_b32 s5, v226, 36
	s_and_b64 s[4:5], s[10:11], s[4:5]
	s_mov_b64 exec, s[4:5]
	s_cbranch_execz .LBB0_409
	v_add_u32_e32 v128, s40, v201
	v_ashrrev_i32_e32 v129, 31, v128
	v_readlane_b32 s4, v226, 37
	v_lshlrev_b64 v[128:129], 6, v[128:129]
	v_readlane_b32 s5, v226, 38
	s_nop 1
	v_lshl_add_u64 v[132:133], s[4:5], 0, v[128:129]
	global_load_dwordx4 v[128:131], v[132:133], off
	global_load_dwordx4 v[140:143], v[132:133], off offset:16
	global_load_dwordx4 v[144:147], v[132:133], off offset:32
	global_load_dwordx4 v[176:179], v[132:133], off offset:48
	s_waitcnt vmcnt(3)
	v_add_f32_e32 v134, v129, v128
	v_add_f32_e32 v135, v130, v131
	v_add_f32_e32 v134, v134, v135
	v_add_f32_e32 v136, 0, v134
	s_waitcnt vmcnt(2)
	v_add_f32_e32 v134, v141, v140
	v_add_f32_e32 v135, v142, v143
	v_add_f32_e32 v134, v134, v135
	v_add_f32_e32 v136, v136, v134
	s_waitcnt vmcnt(1)
	v_add_f32_e32 v134, v145, v144
	v_add_f32_e32 v135, v146, v147
	v_add_f32_e32 v134, v134, v135
	v_add_f32_e32 v136, v136, v134
	s_waitcnt vmcnt(0)
	v_add_f32_e32 v134, v177, v176
	v_add_f32_e32 v135, v178, v179
	v_add_f32_e32 v134, v134, v135
	v_add_f32_e32 v128, v136, v134
	s_nop 0
	v_fmamk_f32 v128, v128, 0x3a800000, v185
	v_rsq_f32_e32 v128, v128
	ds_write_b32 v204, v128

; #define LAS __attribute__((address_space(3)))
; __device__ __forceinline__ void panel_rs_fill(const float* rowss, int pm, LAS float* rs_lds, int tid) {
;     if (tid < 256) {
;         const float* p = rowss + (size_t)(pm * 256 + tid) * 16; float sacc = 0.f;
; #pragma unroll
;         for (int q = 0; q < 4; ++q) { const f32x4 a = *(const f32x4*)(p + 4 * q); sacc += (a[0] + a[1]) + (a[2] + a[3]); asm volatile("" : "+v"(sacc)); }
;         rs_lds[tid] = __builtin_amdgcn_rsqf(sacc * (1.f / 1024.f) + EPS);
;     }
;     asm volatile("s_waitcnt lgkmcnt(0)" ::: "memory"); __builtin_amdgcn_s_barrier(); asm volatile("" ::: "memory");
;     if (tid == 0) ((volatile LAS int*)rs_lds)[256] = pm;
; }
.LBB0_413:
	s_and_b64 vcc, exec, s[10:11]
	s_cbranch_vccz .LBB0_421
	v_readlane_b32 s4, v226, 41
	s_nop 1
	v_mov_b32_e32 v128, s4
	ds_read_b32 v128, v128 offset:1024
	s_waitcnt lgkmcnt(0)
	v_cmp_eq_u32_e32 vcc, s94, v128
	s_cbranch_vccnz .LBB0_420
	s_mov_b64 s[10:11], exec
	v_readlane_b32 s4, v226, 35
	v_readlane_b32 s5, v226, 36
	s_and_b64 s[4:5], s[10:11], s[4:5]
	s_mov_b64 exec, s[4:5]
	s_cbranch_execz .LBB0_417
	v_add_u32_e32 v128, s40, v201
	v_ashrrev_i32_e32 v129, 31, v128
	v_readlane_b32 s4, v226, 42
	v_lshlrev_b64 v[128:129], 6, v[128:129]
	v_readlane_b32 s5, v226, 43
	s_nop 1
	v_lshl_add_u64 v[132:133], s[4:5], 0, v[128:129]
	global_load_dwordx4 v[128:131], v[132:133], off
	global_load_dwordx4 v[140:143], v[132:133], off offset:16
	global_load_dwordx4 v[144:147], v[132:133], off offset:32
	global_load_dwordx4 v[176:179], v[132:133], off offset:48
	s_waitcnt vmcnt(3)
	v_add_f32_e32 v134, v129, v128
	v_add_f32_e32 v135, v130, v131
	v_add_f32_e32 v134, v134, v135
	v_add_f32_e32 v136, 0, v134
	s_waitcnt vmcnt(2)
	v_add_f32_e32 v134, v141, v140
	v_add_f32_e32 v135, v142, v143
	v_add_f32_e32 v134, v134, v135
	v_add_f32_e32 v136, v136, v134
	s_waitcnt vmcnt(1)
	v_add_f32_e32 v134, v145, v144
	v_add_f32_e32 v135, v146, v147
	v_add_f32_e32 v134, v134, v135
	v_add_f32_e32 v136, v136, v134
	s_waitcnt vmcnt(0)
	v_add_f32_e32 v134, v177, v176
	v_add_f32_e32 v135, v178, v179
	v_add_f32_e32 v134, v134, v135
	v_add_f32_e32 v128, v136, v134
	s_nop 0
	v_fmamk_f32 v128, v128, 0x3a800000, v185
	v_rsq_f32_e32 v128, v128
	ds_write_b32 v202, v128
